# v7 plus in-proj tail split: the half-empty 5th tile round is shared by workgroup pairs (each computes 128 rows with a K-loop copy that skips the second row half)
# baseline (speedup 1.0000x reference)
.LBB0_265:
	s_add_i32 s0, s0, 1
	s_mul_i32 s2, s0, s81
	s_mul_hi_u32 s3, s0, s80
	s_add_i32 s3, s3, s2
	s_mul_i32 s2, s0, s80
	s_add_u32 s2, s2, s12
	s_addc_u32 s3, s3, s13
	s_cmp_eq_u32 s24, 18
	s_cbranch_scc0 .Lms_a
	s_cmp_eq_u32 s80, 0x100
	s_cbranch_scc0 .Lms_a
	s_cmp_eq_u32 s0, 4
	s_cbranch_scc0 .Lms_a
	s_and_b32 s2, s12, 0x7f
	s_addk_i32 s2, 0x400
.Lms_a:
	v_mov_b64_e32 v[0:1], s[34:35]
	v_cmp_ge_i64_e32 vcc, s[2:3], v[0:1]
	v_cmp_lt_i64_e64 s[42:43], s[2:3], v[0:1]
	s_cbranch_vccnz .LBB0_267
	s_ashr_i32 s3, s2, 31
	s_lshr_b32 s3, s3, 29
	s_add_i32 s3, s2, s3
	s_ashr_i32 s22, s3, 3
	s_and_b32 s3, s3, -8
	s_sub_i32 s2, s2, s3
	s_lshr_b32 s3, s2, 31
	s_or_b32 s3, s60, s3
	s_mul_i32 s2, s3, s2
	s_add_i32 s2, s2, s22
	s_abs_i32 s22, s2
	s_mul_hi_u32 s23, s22, s1
	s_mul_i32 s25, s23, s19
	s_ashr_i32 s3, s2, 31
	s_sub_i32 s22, s22, s25
	s_xor_b32 s3, s3, s61
	s_add_i32 s25, s23, 1
	s_sub_i32 s40, s22, s19
	s_cmp_ge_u32 s22, s19
	s_cselect_b32 s23, s25, s23
	s_cselect_b32 s22, s40, s22
	s_add_i32 s25, s23, 1
	s_cmp_ge_u32 s22, s19
	s_cselect_b32 s22, s25, s23
	s_xor_b32 s22, s22, s3
	s_sub_i32 s3, s22, s3
	s_lshl_b32 s22, s3, 2
	s_sub_i32 s23, 64, s22
	s_min_i32 s23, s23, 4
	s_abs_i32 s25, s23
	v_cvt_f32_u32_e32 v0, s25
	s_sub_i32 s41, 0, s25
	s_mul_i32 s3, s3, s18
	s_sub_i32 s2, s2, s3
	v_rcp_iflag_f32_e32 v0, v0
	s_abs_i32 s40, s2
	s_xor_b32 s3, s2, s23
	s_ashr_i32 s3, s3, 31
	v_mul_f32_e32 v0, 0x4f7ffffe, v0
	v_cvt_u32_f32_e32 v0, v0
	s_nop 0
	v_readfirstlane_b32 s48, v0
	s_mul_i32 s41, s41, s48
	s_mul_hi_u32 s41, s48, s41
	s_add_i32 s48, s48, s41
	s_mul_hi_u32 s41, s40, s48
	s_mul_i32 s48, s41, s25
	s_sub_i32 s40, s40, s48
	s_add_i32 s48, s41, 1
	s_sub_i32 s50, s40, s25
	s_cmp_ge_u32 s40, s25
	s_cselect_b32 s41, s48, s41
	s_cselect_b32 s40, s50, s40
	s_add_i32 s48, s41, 1
	s_cmp_ge_u32 s40, s25
	s_cselect_b32 s25, s48, s41
	s_xor_b32 s25, s25, s3
	s_sub_i32 s86, s25, s3
	s_mul_i32 s3, s86, s23
	s_sub_i32 s2, s2, s3
	s_add_i32 s23, s2, s22
.LBB0_267:
	s_nop 0
	v_cndmask_b32_e64 v0, 0, 1, s[42:43]
	v_cmp_ne_u32_e64 s[40:41], 1, v0
	s_andn2_b64 vcc, exec, s[42:43]
	s_mov_b32 s25, s45
	s_cbranch_vccnz .LBB0_269
	s_mul_i32 s2, s23, s65
	s_mul_i32 s3, s72, s86
	s_add_i32 s25, s3, s2
	s_lshr_b32 s32, s86, 2
	s_sub_i32 s32, s32, 1
	s_max_i32 s32, s32, 0
	s_lshl_b32 s32, s32, 8
	s_cmp_eq_u32 s16, 3
	s_cselect_b32 s32, s32, 0
	s_add_i32 s25, s25, s32
	s_cmp_eq_u32 s24, 18
	s_cbranch_scc0 .Lms_b
	s_cmp_eq_u32 s80, 0x100
	s_cbranch_scc0 .Lms_b
	s_cmp_eq_u32 s0, 4
	s_cbranch_scc0 .Lms_b
	s_cmp_lt_u32 s12, 0x80
	s_cbranch_scc1 .Lms_b
	s_add_i32 s25, s25, s73
.Lms_b:
.LBB0_269:
	s_mul_i32 s22, s86, s9
	s_lshr_b32 s32, s86, 2
	s_sub_i32 s32, s32, 1
	s_max_i32 s32, s32, 0
	s_lshl_b32 s32, s32, 8
	s_cmp_eq_u32 s16, 3
	s_cselect_b32 s32, s32, 0
	s_add_i32 s22, s22, s32
	s_mov_b32 s101, s54
	s_cmp_eq_u32 s16, 3
	s_cbranch_scc0 .Lkt_nt
	s_lshr_b32 s32, s33, 2
	s_cmp_eq_u32 s32, 2
	s_cselect_b32 s101, 4, 2
.Lkt_nt:
	s_add_i32 s100, s101, -2
	s_and_b64 s[2:3], s[42:43], exec
	v_mov_b32_e32 v0, 0
	s_cselect_b32 s2, s22, s44
	s_add_i32 s3, s45, 0x80
	s_add_i32 s42, s44, 0x100
	s_mov_b32 s43, 0
	v_mov_b32_e32 v1, v0
	v_mov_b32_e32 v2, v0
	v_mov_b32_e32 v3, v0
	v_mov_b32_e32 v4, v0
	v_mov_b32_e32 v5, v0
	v_mov_b32_e32 v6, v0
	v_mov_b32_e32 v7, v0
	v_mov_b32_e32 v16, v0
	v_mov_b32_e32 v17, v0
	v_mov_b32_e32 v18, v0
	v_mov_b32_e32 v19, v0
	v_mov_b32_e32 v20, v0
	v_mov_b32_e32 v21, v0
	v_mov_b32_e32 v22, v0
	v_mov_b32_e32 v23, v0
	v_mov_b32_e32 v32, v0
	v_mov_b32_e32 v33, v0
	v_mov_b32_e32 v34, v0
	v_mov_b32_e32 v35, v0
	v_mov_b32_e32 v36, v0
	v_mov_b32_e32 v37, v0
	v_mov_b32_e32 v38, v0
	v_mov_b32_e32 v39, v0
	v_mov_b32_e32 v48, v0
	v_mov_b32_e32 v49, v0
	v_mov_b32_e32 v50, v0
	v_mov_b32_e32 v51, v0
	v_mov_b32_e32 v52, v0
	v_mov_b32_e32 v53, v0
	v_mov_b32_e32 v54, v0
	v_mov_b32_e32 v55, v0
	v_mov_b32_e32 v8, v0
	v_mov_b32_e32 v9, v0
	v_mov_b32_e32 v10, v0
	v_mov_b32_e32 v11, v0
	v_mov_b32_e32 v12, v0
	v_mov_b32_e32 v13, v0
	v_mov_b32_e32 v14, v0
	v_mov_b32_e32 v15, v0
	v_mov_b32_e32 v24, v0
	v_mov_b32_e32 v25, v0
	v_mov_b32_e32 v26, v0
	v_mov_b32_e32 v27, v0
	v_mov_b32_e32 v28, v0
	v_mov_b32_e32 v29, v0
	v_mov_b32_e32 v30, v0
	v_mov_b32_e32 v31, v0
	v_mov_b32_e32 v40, v0
	v_mov_b32_e32 v41, v0
	v_mov_b32_e32 v42, v0
	v_mov_b32_e32 v43, v0
	v_mov_b32_e32 v44, v0
	v_mov_b32_e32 v45, v0
	v_mov_b32_e32 v46, v0
	v_mov_b32_e32 v47, v0
	v_mov_b32_e32 v56, v0
	v_mov_b32_e32 v57, v0
	v_mov_b32_e32 v58, v0
	v_mov_b32_e32 v59, v0
	v_mov_b32_e32 v60, v0
	v_mov_b32_e32 v61, v0
	v_mov_b32_e32 v62, v0
	v_mov_b32_e32 v63, v0
	v_mov_b32_e32 v64, v0
	v_mov_b32_e32 v65, v0
	v_mov_b32_e32 v66, v0
	v_mov_b32_e32 v67, v0
	v_mov_b32_e32 v68, v0
	v_mov_b32_e32 v69, v0
	v_mov_b32_e32 v70, v0
	v_mov_b32_e32 v71, v0
	v_mov_b32_e32 v80, v0
	v_mov_b32_e32 v81, v0
	v_mov_b32_e32 v82, v0
	v_mov_b32_e32 v83, v0
	v_mov_b32_e32 v84, v0
	v_mov_b32_e32 v85, v0
	v_mov_b32_e32 v86, v0
	v_mov_b32_e32 v87, v0
	v_mov_b32_e32 v96, v0
	v_mov_b32_e32 v97, v0
	v_mov_b32_e32 v98, v0
	v_mov_b32_e32 v99, v0
	v_mov_b32_e32 v100, v0
	v_mov_b32_e32 v101, v0
	v_mov_b32_e32 v102, v0
	v_mov_b32_e32 v103, v0
	v_mov_b32_e32 v112, v0
	v_mov_b32_e32 v113, v0
	v_mov_b32_e32 v114, v0
	v_mov_b32_e32 v115, v0
	v_mov_b32_e32 v116, v0
	v_mov_b32_e32 v117, v0
	v_mov_b32_e32 v118, v0
	v_mov_b32_e32 v119, v0
	v_mov_b32_e32 v72, v0
	v_mov_b32_e32 v73, v0
	v_mov_b32_e32 v74, v0
	v_mov_b32_e32 v75, v0
	v_mov_b32_e32 v76, v0
	v_mov_b32_e32 v77, v0
	v_mov_b32_e32 v78, v0
	v_mov_b32_e32 v79, v0
	v_mov_b32_e32 v88, v0
	v_mov_b32_e32 v89, v0
	v_mov_b32_e32 v90, v0
	v_mov_b32_e32 v91, v0
	v_mov_b32_e32 v92, v0
	v_mov_b32_e32 v93, v0
	v_mov_b32_e32 v94, v0
	v_mov_b32_e32 v95, v0
	v_mov_b32_e32 v104, v0
	v_mov_b32_e32 v105, v0
	v_mov_b32_e32 v106, v0
	v_mov_b32_e32 v107, v0
	v_mov_b32_e32 v108, v0
	v_mov_b32_e32 v109, v0
	v_mov_b32_e32 v110, v0
	v_mov_b32_e32 v111, v0
	v_mov_b32_e32 v120, v0
	v_mov_b32_e32 v121, v0
	v_mov_b32_e32 v122, v0
	v_mov_b32_e32 v123, v0
	v_mov_b32_e32 v124, v0
	v_mov_b32_e32 v125, v0
	v_mov_b32_e32 v126, v0
	v_mov_b32_e32 v127, v0
	s_cmp_eq_u32 s24, 18
	s_cbranch_scc0 .Lms_c
	s_cmp_eq_u32 s80, 0x100
	s_cbranch_scc0 .Lms_c
	s_cmp_eq_u32 s0, 5
	s_cbranch_scc1 .Lhk_loop
.Lms_c:
.LBB0_270:
	v_add_u32_e32 v140, 0x10000, v223
	v_add_u32_e32 v156, 0x14000, v223
	s_waitcnt lgkmcnt(0)
	ds_read_b128 v[128:131], v140
	ds_read_b128 v[132:135], v140 offset:1024
	ds_read_b128 v[136:139], v140 offset:2048
	ds_read_b128 v[140:143], v140 offset:3072
	ds_read_b128 v[144:147], v156
	ds_read_b128 v[148:151], v156 offset:1024
	ds_read_b128 v[152:155], v156 offset:2048
	ds_read_b128 v[182:185], v156 offset:3072
	s_add_i32 s44, s3, 0x80
	s_cmp_eq_u32 s100, s43
	s_cselect_b32 s45, s25, s44
	s_cselect_b32 s90, s2, s42
	s_add_i32 s44, s45, 0x80
	s_add_i32 s48, s73, s3
	s_mov_b32 s76, s46
	s_mov_b32 m0, s96
	ds_read_b128 v[186:189], v224
	ds_read_b128 v[190:193], v224 offset:1024
	ds_read_b128 v[232:235], v224 offset:2048
	ds_read_b128 v[236:239], v224 offset:3072
	ds_read_b128 v[240:243], v224 offset:4096
	ds_read_b128 v[244:247], v224 offset:5120
	ds_read_b128 v[248:251], v224 offset:6144
	ds_read_b128 v[202:205], v224 offset:7168
	buffer_load_dwordx4 v217, s[76:79], s48 offen lds
	s_mov_b32 m0, s97
	s_nop 0
	buffer_load_dwordx4 v219, s[76:79], s48 offen lds
	s_waitcnt vmcnt(8)
	s_waitcnt lgkmcnt(0)
	s_barrier
	s_setprio 1
	s_waitcnt lgkmcnt(7)
	v_mfma_f32_16x16x32_bf16 v[124:127], v[128:131], v[186:189], v[124:127]
	v_mfma_f32_16x16x32_bf16 v[120:123], v[136:139], v[186:189], v[120:123]
	s_waitcnt lgkmcnt(5)
	v_mfma_f32_16x16x32_bf16 v[108:111], v[128:131], v[232:235], v[108:111]
	v_mfma_f32_16x16x32_bf16 v[104:107], v[136:139], v[232:235], v[104:107]
	s_waitcnt lgkmcnt(3)
	v_mfma_f32_16x16x32_bf16 v[92:95], v[128:131], v[240:243], v[92:95]
	v_mfma_f32_16x16x32_bf16 v[88:91], v[136:139], v[240:243], v[88:91]
	s_waitcnt lgkmcnt(1)
	v_mfma_f32_16x16x32_bf16 v[76:79], v[128:131], v[248:251], v[76:79]
	v_mfma_f32_16x16x32_bf16 v[72:75], v[136:139], v[248:251], v[72:75]
	v_mfma_f32_16x16x32_bf16 v[124:127], v[132:135], v[190:193], v[124:127]
	v_mfma_f32_16x16x32_bf16 v[120:123], v[140:143], v[190:193], v[120:123]
	v_mfma_f32_16x16x32_bf16 v[108:111], v[132:135], v[236:239], v[108:111]
	v_mfma_f32_16x16x32_bf16 v[104:107], v[140:143], v[236:239], v[104:107]
	v_mfma_f32_16x16x32_bf16 v[92:95], v[132:135], v[244:247], v[92:95]
	v_mfma_f32_16x16x32_bf16 v[88:91], v[140:143], v[244:247], v[88:91]
	s_waitcnt lgkmcnt(0)
	v_mfma_f32_16x16x32_bf16 v[76:79], v[132:135], v[202:205], v[76:79]
	v_mfma_f32_16x16x32_bf16 v[72:75], v[140:143], v[202:205], v[72:75]
	s_setprio 0
	s_setprio 1
	v_mfma_f32_16x16x32_bf16 v[116:119], v[144:147], v[186:189], v[116:119]
	v_mfma_f32_16x16x32_bf16 v[112:115], v[152:155], v[186:189], v[112:115]
	v_mfma_f32_16x16x32_bf16 v[100:103], v[144:147], v[232:235], v[100:103]
	v_mfma_f32_16x16x32_bf16 v[96:99], v[152:155], v[232:235], v[96:99]
	v_mfma_f32_16x16x32_bf16 v[84:87], v[144:147], v[240:243], v[84:87]
	v_mfma_f32_16x16x32_bf16 v[80:83], v[152:155], v[240:243], v[80:83]
	v_mfma_f32_16x16x32_bf16 v[68:71], v[144:147], v[248:251], v[68:71]
	v_mfma_f32_16x16x32_bf16 v[64:67], v[152:155], v[248:251], v[64:67]
	v_mfma_f32_16x16x32_bf16 v[116:119], v[148:151], v[190:193], v[116:119]
	v_mfma_f32_16x16x32_bf16 v[112:115], v[182:185], v[190:193], v[112:115]
	v_mfma_f32_16x16x32_bf16 v[100:103], v[148:151], v[236:239], v[100:103]
	v_mfma_f32_16x16x32_bf16 v[96:99], v[182:185], v[236:239], v[96:99]
	v_mfma_f32_16x16x32_bf16 v[84:87], v[148:151], v[244:247], v[84:87]
	v_mfma_f32_16x16x32_bf16 v[80:83], v[182:185], v[244:247], v[80:83]
	v_mfma_f32_16x16x32_bf16 v[68:71], v[148:151], v[202:205], v[68:71]
	v_mfma_f32_16x16x32_bf16 v[64:67], v[182:185], v[202:205], v[64:67]
	s_setprio 0
	s_barrier
	s_mov_b32 m0, s71
	s_mov_b32 s48, s94
	s_mov_b32 s50, s78
	s_mov_b32 s51, s79
	ds_read_b128 v[186:189], v224 offset:16384
	ds_read_b128 v[190:193], v224 offset:17408
	ds_read_b128 v[202:205], v224 offset:18432
	ds_read_b128 v[232:235], v224 offset:19456
	ds_read_b128 v[236:239], v224 offset:20480
	ds_read_b128 v[240:243], v224 offset:21504
	ds_read_b128 v[244:247], v224 offset:22528
	ds_read_b128 v[248:251], v224 offset:23552
	buffer_load_dwordx4 v218, s[48:51], s90 offen lds
	s_mov_b32 m0, s28
	s_add_i32 s91, s90, s64
	buffer_load_dwordx4 v220, s[48:51], s90 offen lds
	s_mov_b32 m0, s29
	s_nop 0
	buffer_load_dwordx4 v218, s[48:51], s91 offen lds
	s_mov_b32 m0, s26
	s_nop 0
	buffer_load_dwordx4 v220, s[48:51], s91 offen lds
	s_mov_b32 m0, s70
	s_nop 0
	buffer_load_dwordx4 v217, s[76:79], s45 offen lds
	s_mov_b32 m0, s27
	s_nop 0
	buffer_load_dwordx4 v219, s[76:79], s45 offen lds
	s_waitcnt vmcnt(8)
	s_waitcnt lgkmcnt(0)
	s_barrier
	s_setprio 1
	s_waitcnt lgkmcnt(7)
	v_mfma_f32_16x16x32_bf16 v[60:63], v[128:131], v[186:189], v[60:63]
	v_mfma_f32_16x16x32_bf16 v[56:59], v[136:139], v[186:189], v[56:59]
	s_waitcnt lgkmcnt(5)
	v_mfma_f32_16x16x32_bf16 v[44:47], v[128:131], v[202:205], v[44:47]
	v_mfma_f32_16x16x32_bf16 v[40:43], v[136:139], v[202:205], v[40:43]
	s_waitcnt lgkmcnt(3)
	v_mfma_f32_16x16x32_bf16 v[28:31], v[128:131], v[236:239], v[28:31]
	v_mfma_f32_16x16x32_bf16 v[24:27], v[136:139], v[236:239], v[24:27]
	s_waitcnt lgkmcnt(1)
	v_mfma_f32_16x16x32_bf16 v[12:15], v[128:131], v[244:247], v[12:15]
	v_mfma_f32_16x16x32_bf16 v[8:11], v[136:139], v[244:247], v[8:11]
	v_mfma_f32_16x16x32_bf16 v[60:63], v[132:135], v[190:193], v[60:63]
	v_mfma_f32_16x16x32_bf16 v[56:59], v[140:143], v[190:193], v[56:59]
	v_mfma_f32_16x16x32_bf16 v[44:47], v[132:135], v[232:235], v[44:47]
	v_mfma_f32_16x16x32_bf16 v[40:43], v[140:143], v[232:235], v[40:43]
	v_mfma_f32_16x16x32_bf16 v[28:31], v[132:135], v[240:243], v[28:31]
	v_mfma_f32_16x16x32_bf16 v[24:27], v[140:143], v[240:243], v[24:27]
	s_waitcnt lgkmcnt(0)
	v_mfma_f32_16x16x32_bf16 v[12:15], v[132:135], v[248:251], v[12:15]
	v_mfma_f32_16x16x32_bf16 v[8:11], v[140:143], v[248:251], v[8:11]
	s_setprio 0
	s_setprio 1
	v_mfma_f32_16x16x32_bf16 v[52:55], v[144:147], v[186:189], v[52:55]
	v_mfma_f32_16x16x32_bf16 v[48:51], v[152:155], v[186:189], v[48:51]
	v_mfma_f32_16x16x32_bf16 v[36:39], v[144:147], v[202:205], v[36:39]
	v_mfma_f32_16x16x32_bf16 v[32:35], v[152:155], v[202:205], v[32:35]
	v_mfma_f32_16x16x32_bf16 v[20:23], v[144:147], v[236:239], v[20:23]
	v_mfma_f32_16x16x32_bf16 v[16:19], v[152:155], v[236:239], v[16:19]
	v_mfma_f32_16x16x32_bf16 v[4:7], v[144:147], v[244:247], v[4:7]
	v_mfma_f32_16x16x32_bf16 v[0:3], v[152:155], v[244:247], v[0:3]
	v_mfma_f32_16x16x32_bf16 v[52:55], v[148:151], v[190:193], v[52:55]
	v_mfma_f32_16x16x32_bf16 v[48:51], v[182:185], v[190:193], v[48:51]
	v_mfma_f32_16x16x32_bf16 v[36:39], v[148:151], v[232:235], v[36:39]
	v_mfma_f32_16x16x32_bf16 v[32:35], v[182:185], v[232:235], v[32:35]
	v_mfma_f32_16x16x32_bf16 v[20:23], v[148:151], v[240:243], v[20:23]
	v_mfma_f32_16x16x32_bf16 v[16:19], v[182:185], v[240:243], v[16:19]
	v_mfma_f32_16x16x32_bf16 v[4:7], v[148:151], v[248:251], v[4:7]
	v_mfma_f32_16x16x32_bf16 v[0:3], v[182:185], v[248:251], v[0:3]
	s_setprio 0
	s_barrier
	v_add_u32_e32 v140, 0x18000, v223
	v_add_u32_e32 v156, 0x1c000, v223
	ds_read_b128 v[128:131], v140
	ds_read_b128 v[132:135], v140 offset:1024
	ds_read_b128 v[136:139], v140 offset:2048
	ds_read_b128 v[140:143], v140 offset:3072
	ds_read_b128 v[144:147], v156
	ds_read_b128 v[148:151], v156 offset:1024
	ds_read_b128 v[152:155], v156 offset:2048
	ds_read_b128 v[182:185], v156 offset:3072
	s_add_i32 s45, s45, s73
	s_mov_b32 m0, s62
	ds_read_b128 v[186:189], v224 offset:32768
	ds_read_b128 v[190:193], v224 offset:33792
	ds_read_b128 v[202:205], v224 offset:34816
	ds_read_b128 v[232:235], v224 offset:35840
	ds_read_b128 v[236:239], v224 offset:36864
	ds_read_b128 v[240:243], v224 offset:37888
	ds_read_b128 v[244:247], v224 offset:38912
	ds_read_b128 v[248:251], v224 offset:39936
	buffer_load_dwordx4 v217, s[76:79], s45 offen lds
	s_mov_b32 m0, s63
	s_nop 0
	buffer_load_dwordx4 v219, s[76:79], s45 offen lds
	s_waitcnt vmcnt(8)
	s_waitcnt lgkmcnt(0)
	s_barrier
	s_setprio 1
	s_waitcnt lgkmcnt(7)
	v_mfma_f32_16x16x32_bf16 v[124:127], v[128:131], v[186:189], v[124:127]
	v_mfma_f32_16x16x32_bf16 v[120:123], v[136:139], v[186:189], v[120:123]
	s_waitcnt lgkmcnt(5)
	v_mfma_f32_16x16x32_bf16 v[108:111], v[128:131], v[202:205], v[108:111]
	v_mfma_f32_16x16x32_bf16 v[104:107], v[136:139], v[202:205], v[104:107]
	s_waitcnt lgkmcnt(3)
	v_mfma_f32_16x16x32_bf16 v[92:95], v[128:131], v[236:239], v[92:95]
	v_mfma_f32_16x16x32_bf16 v[88:91], v[136:139], v[236:239], v[88:91]
	s_waitcnt lgkmcnt(1)
	v_mfma_f32_16x16x32_bf16 v[76:79], v[128:131], v[244:247], v[76:79]
	v_mfma_f32_16x16x32_bf16 v[72:75], v[136:139], v[244:247], v[72:75]
	v_mfma_f32_16x16x32_bf16 v[124:127], v[132:135], v[190:193], v[124:127]
	v_mfma_f32_16x16x32_bf16 v[120:123], v[140:143], v[190:193], v[120:123]
	v_mfma_f32_16x16x32_bf16 v[108:111], v[132:135], v[232:235], v[108:111]
	v_mfma_f32_16x16x32_bf16 v[104:107], v[140:143], v[232:235], v[104:107]
	v_mfma_f32_16x16x32_bf16 v[92:95], v[132:135], v[240:243], v[92:95]
	v_mfma_f32_16x16x32_bf16 v[88:91], v[140:143], v[240:243], v[88:91]
	s_waitcnt lgkmcnt(0)
	v_mfma_f32_16x16x32_bf16 v[76:79], v[132:135], v[248:251], v[76:79]
	v_mfma_f32_16x16x32_bf16 v[72:75], v[140:143], v[248:251], v[72:75]
	s_setprio 0
	s_setprio 1
	v_mfma_f32_16x16x32_bf16 v[116:119], v[144:147], v[186:189], v[116:119]
	v_mfma_f32_16x16x32_bf16 v[112:115], v[152:155], v[186:189], v[112:115]
	v_mfma_f32_16x16x32_bf16 v[100:103], v[144:147], v[202:205], v[100:103]
	v_mfma_f32_16x16x32_bf16 v[96:99], v[152:155], v[202:205], v[96:99]
	v_mfma_f32_16x16x32_bf16 v[84:87], v[144:147], v[236:239], v[84:87]
	v_mfma_f32_16x16x32_bf16 v[80:83], v[152:155], v[236:239], v[80:83]
	v_mfma_f32_16x16x32_bf16 v[68:71], v[144:147], v[244:247], v[68:71]
	v_mfma_f32_16x16x32_bf16 v[64:67], v[152:155], v[244:247], v[64:67]
	v_mfma_f32_16x16x32_bf16 v[116:119], v[148:151], v[190:193], v[116:119]
	v_mfma_f32_16x16x32_bf16 v[112:115], v[182:185], v[190:193], v[112:115]
	v_mfma_f32_16x16x32_bf16 v[100:103], v[148:151], v[232:235], v[100:103]
	v_mfma_f32_16x16x32_bf16 v[96:99], v[182:185], v[232:235], v[96:99]
	v_mfma_f32_16x16x32_bf16 v[84:87], v[148:151], v[240:243], v[84:87]
	v_mfma_f32_16x16x32_bf16 v[80:83], v[182:185], v[240:243], v[80:83]
	v_mfma_f32_16x16x32_bf16 v[68:71], v[148:151], v[248:251], v[68:71]
	v_mfma_f32_16x16x32_bf16 v[64:67], v[182:185], v[248:251], v[64:67]
	s_setprio 0
	s_barrier
	s_mov_b32 m0, s88
	s_add_i32 s45, s90, 0x80
	ds_read_b128 v[186:189], v224 offset:49152
	ds_read_b128 v[190:193], v224 offset:50176
	ds_read_b128 v[202:205], v224 offset:51200
	ds_read_b128 v[232:235], v224 offset:52224
	ds_read_b128 v[236:239], v224 offset:53248
	ds_read_b128 v[240:243], v224 offset:54272
	ds_read_b128 v[244:247], v224 offset:55296
	ds_read_b128 v[248:251], v224 offset:56320
	buffer_load_dwordx4 v218, s[48:51], s45 offen lds
	s_mov_b32 m0, s82
	s_nop 0
	buffer_load_dwordx4 v220, s[48:51], s45 offen lds
	s_add_i32 s45, s45, s64
	s_mov_b32 m0, s58
	s_nop 0
	buffer_load_dwordx4 v218, s[48:51], s45 offen lds
	s_mov_b32 m0, s59
	s_nop 0
	buffer_load_dwordx4 v220, s[48:51], s45 offen lds
	s_mov_b32 m0, s83
	s_nop 0
	buffer_load_dwordx4 v217, s[76:79], s44 offen lds
	s_mov_b32 m0, s89
	s_nop 0
	buffer_load_dwordx4 v219, s[76:79], s44 offen lds
	s_waitcnt vmcnt(8)
	s_waitcnt lgkmcnt(0)
	s_barrier
	s_setprio 1
	s_waitcnt lgkmcnt(7)
	v_mfma_f32_16x16x32_bf16 v[60:63], v[128:131], v[186:189], v[60:63]
	v_mfma_f32_16x16x32_bf16 v[56:59], v[136:139], v[186:189], v[56:59]
	s_waitcnt lgkmcnt(5)
	v_mfma_f32_16x16x32_bf16 v[44:47], v[128:131], v[202:205], v[44:47]
	v_mfma_f32_16x16x32_bf16 v[40:43], v[136:139], v[202:205], v[40:43]
	s_waitcnt lgkmcnt(3)
	v_mfma_f32_16x16x32_bf16 v[28:31], v[128:131], v[236:239], v[28:31]
	v_mfma_f32_16x16x32_bf16 v[24:27], v[136:139], v[236:239], v[24:27]
	s_waitcnt lgkmcnt(1)
	v_mfma_f32_16x16x32_bf16 v[12:15], v[128:131], v[244:247], v[12:15]
	v_mfma_f32_16x16x32_bf16 v[8:11], v[136:139], v[244:247], v[8:11]
	v_mfma_f32_16x16x32_bf16 v[60:63], v[132:135], v[190:193], v[60:63]
	v_mfma_f32_16x16x32_bf16 v[56:59], v[140:143], v[190:193], v[56:59]
	v_mfma_f32_16x16x32_bf16 v[44:47], v[132:135], v[232:235], v[44:47]
	v_mfma_f32_16x16x32_bf16 v[40:43], v[140:143], v[232:235], v[40:43]
	v_mfma_f32_16x16x32_bf16 v[28:31], v[132:135], v[240:243], v[28:31]
	v_mfma_f32_16x16x32_bf16 v[24:27], v[140:143], v[240:243], v[24:27]
	s_waitcnt lgkmcnt(0)
	v_mfma_f32_16x16x32_bf16 v[12:15], v[132:135], v[248:251], v[12:15]
	v_mfma_f32_16x16x32_bf16 v[8:11], v[140:143], v[248:251], v[8:11]
	s_setprio 0
	s_setprio 1
	v_mfma_f32_16x16x32_bf16 v[52:55], v[144:147], v[186:189], v[52:55]
	v_mfma_f32_16x16x32_bf16 v[48:51], v[152:155], v[186:189], v[48:51]
	v_mfma_f32_16x16x32_bf16 v[36:39], v[144:147], v[202:205], v[36:39]
	v_mfma_f32_16x16x32_bf16 v[32:35], v[152:155], v[202:205], v[32:35]
	v_mfma_f32_16x16x32_bf16 v[20:23], v[144:147], v[236:239], v[20:23]
	v_mfma_f32_16x16x32_bf16 v[16:19], v[152:155], v[236:239], v[16:19]
	v_mfma_f32_16x16x32_bf16 v[4:7], v[144:147], v[244:247], v[4:7]
	v_mfma_f32_16x16x32_bf16 v[0:3], v[152:155], v[244:247], v[0:3]
	v_mfma_f32_16x16x32_bf16 v[52:55], v[148:151], v[190:193], v[52:55]
	v_mfma_f32_16x16x32_bf16 v[48:51], v[182:185], v[190:193], v[48:51]
	v_mfma_f32_16x16x32_bf16 v[36:39], v[148:151], v[232:235], v[36:39]
	v_mfma_f32_16x16x32_bf16 v[32:35], v[182:185], v[232:235], v[32:35]
	v_mfma_f32_16x16x32_bf16 v[20:23], v[148:151], v[240:243], v[20:23]
	v_mfma_f32_16x16x32_bf16 v[16:19], v[182:185], v[240:243], v[16:19]
	v_mfma_f32_16x16x32_bf16 v[4:7], v[148:151], v[248:251], v[4:7]
	v_mfma_f32_16x16x32_bf16 v[0:3], v[182:185], v[248:251], v[0:3]
	s_setprio 0
	s_barrier
	s_add_i32 s43, s43, 2
	s_addk_i32 s3, 0x100
	s_addk_i32 s42, 0x100
	s_cmp_ge_i32 s43, s101
	s_cbranch_scc0 .LBB0_270
	s_mov_b32 s32, 0
	s_branch .Lhk_join
.Lhk_loop:
	v_add_u32_e32 v140, 0x10000, v223
	v_add_u32_e32 v156, 0x14000, v223
	s_waitcnt lgkmcnt(0)
	ds_read_b128 v[128:131], v140
	ds_read_b128 v[132:135], v140 offset:1024
	ds_read_b128 v[136:139], v140 offset:2048
	ds_read_b128 v[140:143], v140 offset:3072
	ds_read_b128 v[144:147], v156
	ds_read_b128 v[148:151], v156 offset:1024
	ds_read_b128 v[152:155], v156 offset:2048
	ds_read_b128 v[182:185], v156 offset:3072
	s_add_i32 s44, s3, 0x80
	s_cmp_eq_u32 s100, s43
	s_cselect_b32 s45, s25, s44
	s_cselect_b32 s90, s2, s42
	s_add_i32 s44, s45, 0x80
	s_add_i32 s48, s73, s3
	s_mov_b32 s76, s46
	s_mov_b32 m0, s96
	ds_read_b128 v[186:189], v224
	ds_read_b128 v[190:193], v224 offset:1024
	ds_read_b128 v[232:235], v224 offset:2048
	ds_read_b128 v[236:239], v224 offset:3072
	ds_read_b128 v[240:243], v224 offset:4096
	ds_read_b128 v[244:247], v224 offset:5120
	ds_read_b128 v[248:251], v224 offset:6144
	ds_read_b128 v[202:205], v224 offset:7168
	s_mov_b32 m0, s97
	s_nop 0
	s_waitcnt vmcnt(6)
	s_waitcnt lgkmcnt(0)
	s_barrier
	s_setprio 1
	s_waitcnt lgkmcnt(7)
	v_mfma_f32_16x16x32_bf16 v[124:127], v[128:131], v[186:189], v[124:127]
	v_mfma_f32_16x16x32_bf16 v[120:123], v[136:139], v[186:189], v[120:123]
	s_waitcnt lgkmcnt(5)
	v_mfma_f32_16x16x32_bf16 v[108:111], v[128:131], v[232:235], v[108:111]
	v_mfma_f32_16x16x32_bf16 v[104:107], v[136:139], v[232:235], v[104:107]
	s_waitcnt lgkmcnt(3)
	v_mfma_f32_16x16x32_bf16 v[92:95], v[128:131], v[240:243], v[92:95]
	v_mfma_f32_16x16x32_bf16 v[88:91], v[136:139], v[240:243], v[88:91]
	s_waitcnt lgkmcnt(1)
	v_mfma_f32_16x16x32_bf16 v[76:79], v[128:131], v[248:251], v[76:79]
	v_mfma_f32_16x16x32_bf16 v[72:75], v[136:139], v[248:251], v[72:75]
	v_mfma_f32_16x16x32_bf16 v[124:127], v[132:135], v[190:193], v[124:127]
	v_mfma_f32_16x16x32_bf16 v[120:123], v[140:143], v[190:193], v[120:123]
	v_mfma_f32_16x16x32_bf16 v[108:111], v[132:135], v[236:239], v[108:111]
	v_mfma_f32_16x16x32_bf16 v[104:107], v[140:143], v[236:239], v[104:107]
	v_mfma_f32_16x16x32_bf16 v[92:95], v[132:135], v[244:247], v[92:95]
	v_mfma_f32_16x16x32_bf16 v[88:91], v[140:143], v[244:247], v[88:91]
	s_waitcnt lgkmcnt(0)
	v_mfma_f32_16x16x32_bf16 v[76:79], v[132:135], v[202:205], v[76:79]
	v_mfma_f32_16x16x32_bf16 v[72:75], v[140:143], v[202:205], v[72:75]
	s_setprio 0
	s_setprio 1
	v_mfma_f32_16x16x32_bf16 v[116:119], v[144:147], v[186:189], v[116:119]
	v_mfma_f32_16x16x32_bf16 v[112:115], v[152:155], v[186:189], v[112:115]
	v_mfma_f32_16x16x32_bf16 v[100:103], v[144:147], v[232:235], v[100:103]
	v_mfma_f32_16x16x32_bf16 v[96:99], v[152:155], v[232:235], v[96:99]
	v_mfma_f32_16x16x32_bf16 v[84:87], v[144:147], v[240:243], v[84:87]
	v_mfma_f32_16x16x32_bf16 v[80:83], v[152:155], v[240:243], v[80:83]
	v_mfma_f32_16x16x32_bf16 v[68:71], v[144:147], v[248:251], v[68:71]
	v_mfma_f32_16x16x32_bf16 v[64:67], v[152:155], v[248:251], v[64:67]
	v_mfma_f32_16x16x32_bf16 v[116:119], v[148:151], v[190:193], v[116:119]
	v_mfma_f32_16x16x32_bf16 v[112:115], v[182:185], v[190:193], v[112:115]
	v_mfma_f32_16x16x32_bf16 v[100:103], v[148:151], v[236:239], v[100:103]
	v_mfma_f32_16x16x32_bf16 v[96:99], v[182:185], v[236:239], v[96:99]
	v_mfma_f32_16x16x32_bf16 v[84:87], v[148:151], v[244:247], v[84:87]
	v_mfma_f32_16x16x32_bf16 v[80:83], v[182:185], v[244:247], v[80:83]
	v_mfma_f32_16x16x32_bf16 v[68:71], v[148:151], v[202:205], v[68:71]
	v_mfma_f32_16x16x32_bf16 v[64:67], v[182:185], v[202:205], v[64:67]
	s_setprio 0
	s_barrier
	s_mov_b32 m0, s71
	s_mov_b32 s48, s94
	s_mov_b32 s50, s78
	s_mov_b32 s51, s79
	buffer_load_dwordx4 v218, s[48:51], s90 offen lds
	s_mov_b32 m0, s28
	s_add_i32 s91, s90, s64
	buffer_load_dwordx4 v220, s[48:51], s90 offen lds
	s_mov_b32 m0, s29
	s_nop 0
	buffer_load_dwordx4 v218, s[48:51], s91 offen lds
	s_mov_b32 m0, s26
	s_nop 0
	buffer_load_dwordx4 v220, s[48:51], s91 offen lds
	s_mov_b32 m0, s70
	s_nop 0
	buffer_load_dwordx4 v217, s[76:79], s45 offen lds
	s_mov_b32 m0, s27
	s_nop 0
	buffer_load_dwordx4 v219, s[76:79], s45 offen lds
	s_waitcnt vmcnt(6)
	s_waitcnt lgkmcnt(0)
	s_barrier
	s_setprio 1
	s_waitcnt lgkmcnt(7)
	s_waitcnt lgkmcnt(5)
	s_waitcnt lgkmcnt(3)
	s_waitcnt lgkmcnt(1)
	s_waitcnt lgkmcnt(0)
	s_setprio 0
	s_setprio 1
	s_setprio 0
	s_barrier
	v_add_u32_e32 v140, 0x18000, v223
	v_add_u32_e32 v156, 0x1c000, v223
	ds_read_b128 v[128:131], v140
	ds_read_b128 v[132:135], v140 offset:1024
	ds_read_b128 v[136:139], v140 offset:2048
	ds_read_b128 v[140:143], v140 offset:3072
	ds_read_b128 v[144:147], v156
	ds_read_b128 v[148:151], v156 offset:1024
	ds_read_b128 v[152:155], v156 offset:2048
	ds_read_b128 v[182:185], v156 offset:3072
	s_add_i32 s45, s45, s73
	s_mov_b32 m0, s62
	ds_read_b128 v[186:189], v224 offset:32768
	ds_read_b128 v[190:193], v224 offset:33792
	ds_read_b128 v[202:205], v224 offset:34816
	ds_read_b128 v[232:235], v224 offset:35840
	ds_read_b128 v[236:239], v224 offset:36864
	ds_read_b128 v[240:243], v224 offset:37888
	ds_read_b128 v[244:247], v224 offset:38912
	ds_read_b128 v[248:251], v224 offset:39936
	s_mov_b32 m0, s63
	s_nop 0
	s_waitcnt vmcnt(6)
	s_waitcnt lgkmcnt(0)
	s_barrier
	s_setprio 1
	s_waitcnt lgkmcnt(7)
	v_mfma_f32_16x16x32_bf16 v[124:127], v[128:131], v[186:189], v[124:127]
	v_mfma_f32_16x16x32_bf16 v[120:123], v[136:139], v[186:189], v[120:123]
	s_waitcnt lgkmcnt(5)
	v_mfma_f32_16x16x32_bf16 v[108:111], v[128:131], v[202:205], v[108:111]
	v_mfma_f32_16x16x32_bf16 v[104:107], v[136:139], v[202:205], v[104:107]
	s_waitcnt lgkmcnt(3)
	v_mfma_f32_16x16x32_bf16 v[92:95], v[128:131], v[236:239], v[92:95]
	v_mfma_f32_16x16x32_bf16 v[88:91], v[136:139], v[236:239], v[88:91]
	s_waitcnt lgkmcnt(1)
	v_mfma_f32_16x16x32_bf16 v[76:79], v[128:131], v[244:247], v[76:79]
	v_mfma_f32_16x16x32_bf16 v[72:75], v[136:139], v[244:247], v[72:75]
	v_mfma_f32_16x16x32_bf16 v[124:127], v[132:135], v[190:193], v[124:127]
	v_mfma_f32_16x16x32_bf16 v[120:123], v[140:143], v[190:193], v[120:123]
	v_mfma_f32_16x16x32_bf16 v[108:111], v[132:135], v[232:235], v[108:111]
	v_mfma_f32_16x16x32_bf16 v[104:107], v[140:143], v[232:235], v[104:107]
	v_mfma_f32_16x16x32_bf16 v[92:95], v[132:135], v[240:243], v[92:95]
	v_mfma_f32_16x16x32_bf16 v[88:91], v[140:143], v[240:243], v[88:91]
	s_waitcnt lgkmcnt(0)
	v_mfma_f32_16x16x32_bf16 v[76:79], v[132:135], v[248:251], v[76:79]
	v_mfma_f32_16x16x32_bf16 v[72:75], v[140:143], v[248:251], v[72:75]
	s_setprio 0
	s_setprio 1
	v_mfma_f32_16x16x32_bf16 v[116:119], v[144:147], v[186:189], v[116:119]
	v_mfma_f32_16x16x32_bf16 v[112:115], v[152:155], v[186:189], v[112:115]
	v_mfma_f32_16x16x32_bf16 v[100:103], v[144:147], v[202:205], v[100:103]
	v_mfma_f32_16x16x32_bf16 v[96:99], v[152:155], v[202:205], v[96:99]
	v_mfma_f32_16x16x32_bf16 v[84:87], v[144:147], v[236:239], v[84:87]
	v_mfma_f32_16x16x32_bf16 v[80:83], v[152:155], v[236:239], v[80:83]
	v_mfma_f32_16x16x32_bf16 v[68:71], v[144:147], v[244:247], v[68:71]
	v_mfma_f32_16x16x32_bf16 v[64:67], v[152:155], v[244:247], v[64:67]
	v_mfma_f32_16x16x32_bf16 v[116:119], v[148:151], v[190:193], v[116:119]
	v_mfma_f32_16x16x32_bf16 v[112:115], v[182:185], v[190:193], v[112:115]
	v_mfma_f32_16x16x32_bf16 v[100:103], v[148:151], v[232:235], v[100:103]
	v_mfma_f32_16x16x32_bf16 v[96:99], v[182:185], v[232:235], v[96:99]
	v_mfma_f32_16x16x32_bf16 v[84:87], v[148:151], v[240:243], v[84:87]
	v_mfma_f32_16x16x32_bf16 v[80:83], v[182:185], v[240:243], v[80:83]
	v_mfma_f32_16x16x32_bf16 v[68:71], v[148:151], v[248:251], v[68:71]
	v_mfma_f32_16x16x32_bf16 v[64:67], v[182:185], v[248:251], v[64:67]
	s_setprio 0
	s_barrier
	s_mov_b32 m0, s88
	s_add_i32 s45, s90, 0x80
	buffer_load_dwordx4 v218, s[48:51], s45 offen lds
	s_mov_b32 m0, s82
	s_nop 0
	buffer_load_dwordx4 v220, s[48:51], s45 offen lds
	s_add_i32 s45, s45, s64
	s_mov_b32 m0, s58
	s_nop 0
	buffer_load_dwordx4 v218, s[48:51], s45 offen lds
	s_mov_b32 m0, s59
	s_nop 0
	buffer_load_dwordx4 v220, s[48:51], s45 offen lds
	s_mov_b32 m0, s83
	s_nop 0
	buffer_load_dwordx4 v217, s[76:79], s44 offen lds
	s_mov_b32 m0, s89
	s_nop 0
	buffer_load_dwordx4 v219, s[76:79], s44 offen lds
	s_waitcnt vmcnt(6)
	s_waitcnt lgkmcnt(0)
	s_barrier
	s_setprio 1
	s_waitcnt lgkmcnt(7)
	s_waitcnt lgkmcnt(5)
	s_waitcnt lgkmcnt(3)
	s_waitcnt lgkmcnt(1)
	s_waitcnt lgkmcnt(0)
	s_setprio 0
	s_setprio 1
	s_setprio 0
	s_barrier
	s_add_i32 s43, s43, 2
	s_addk_i32 s3, 0x100
	s_addk_i32 s42, 0x100
	s_cmp_ge_i32 s43, s101
	s_cbranch_scc0 .Lhk_loop
	s_mov_b32 s100, -1
	s_mov_b32 s32, 0
	s_cmp_lt_u32 s12, 0x80
	s_cbranch_scc1 .Lhk_join
	s_movk_i32 s32, 0x80
.Lhk_join:
	s_and_b64 vcc, exec, s[20:21]
	s_cbranch_vccz .LBB0_273
	s_barrier

.LBB0_455:
.LBB0_456:
	s_and_b64 vcc, exec, s[90:91]
	v_lshl_add_u32 v144, s87, 8, v221
	v_add_u32_e32 v144, s32, v144
	v_lshl_or_b32 v146, s33, 8, v222
	s_cbranch_vccz .LBB0_474
	v_ashrrev_i32_e32 v147, 31, v146
	v_ashrrev_i32_e32 v145, 31, v144
	v_mul_lo_u32 v152, s14, v145
	v_mul_lo_u32 v138, s15, v144
	s_waitcnt lgkmcnt(0)
	v_mad_u64_u32 v[128:129], s[2:3], s14, v144, v[146:147]
	v_add3_u32 v129, v138, v129, v152
	v_lshlrev_b64 v[128:129], 1, v[128:129]
	v_lshl_add_u64 v[130:131], s[6:7], 0, v[128:129]
	v_lshl_add_u64 v[128:129], s[56:57], 0, v[128:129]
	global_load_dwordx4 v[182:185], v[130:131], off
	global_load_dwordx4 v[186:189], v[128:129], off
	global_load_dwordx4 v[190:193], v[130:131], off offset:256
	global_load_dwordx4 v[202:205], v[128:129], off offset:256
	s_waitcnt vmcnt(27)
	v_ffbh_u32_e32 v132, v181
	s_waitcnt vmcnt(26)
	v_ffbh_u32_e32 v133, v179
	v_or_b32_e32 v153, 16, v144
	v_min_u32_e32 v136, 32, v132
	v_min_u32_e32 v139, 32, v133
	v_mul_lo_u32 v154, s15, v153
	v_mad_u64_u32 v[132:133], s[2:3], s14, v153, v[146:147]
	v_lshlrev_b64 v[134:135], v136, v[180:181]
	v_sub_u32_e32 v140, 32, v136
	v_lshlrev_b64 v[136:137], v139, v[178:179]
	v_mad_u64_u32 v[148:149], s[2:3], s14, v144, 0
	v_add3_u32 v133, v154, v133, v152
	v_min_u32_e32 v134, 1, v134
	v_min_u32_e32 v136, 1, v136
	v_add3_u32 v149, v149, v152, v138
	v_lshlrev_b64 v[132:133], 1, v[132:133]
	v_or_b32_e32 v138, v135, v134
	v_or_b32_e32 v136, v137, v136
	v_lshl_add_u64 v[134:135], s[6:7], 0, v[132:133]
	v_lshl_add_u64 v[194:195], s[56:57], 0, v[132:133]
	v_cvt_f32_u32_e32 v132, v138
	v_cvt_f32_u32_e32 v133, v136
	v_sub_u32_e32 v139, 32, v139
	v_lshl_add_u64 v[148:149], v[148:149], 1, s[68:69]
	v_ldexp_f32 v129, v132, v140
	v_ldexp_f32 v128, v133, v139
	v_pk_fma_f32 v[150:151], v[128:129], s[36:37], v[158:159] op_sel_hi:[1,0,0]
	v_lshl_add_u64 v[148:149], v[146:147], 1, v[148:149]
	v_mul_f32_e32 v128, 0x4b800000, v151
	v_cmp_gt_f32_e32 vcc, s37, v151
	s_waitcnt vmcnt(3)
	v_lshlrev_b32_e32 v238, 16, v184
	v_cndmask_b32_e32 v128, v151, v128, vcc
	v_rsq_f32_e32 v151, v128
	global_load_dwordx4 v[136:139], v[134:135], off
	s_nop 0
	global_load_dwordx4 v[132:135], v[134:135], off offset:256
	s_nop 0
	global_load_dwordx4 v[140:143], v[194:195], off
	global_load_dwordx4 v[128:131], v[194:195], off offset:256
	v_and_b32_e32 v184, 0xffff0000, v184
	v_lshlrev_b32_e32 v239, 16, v185
	v_mul_f32_e32 v155, 0x45800000, v151
	v_cndmask_b32_e32 v156, v151, v155, vcc
	v_pk_mul_f32 v[194:195], v[156:157], v[126:127] op_sel_hi:[0,1]
	v_pk_mul_f32 v[232:233], v[156:157], v[124:125] op_sel_hi:[0,1]
	v_pk_mul_f32 v[234:235], v[156:157], v[122:123] op_sel_hi:[0,1]
	v_pk_mul_f32 v[236:237], v[156:157], v[120:121] op_sel_hi:[0,1]
	v_mul_f32_e32 v151, 0xbfb8aa3b, v232
	v_mul_f32_e32 v232, 0xbfb8aa3b, v233
	v_mul_f32_e32 v233, 0xbfb8aa3b, v237
	v_mul_f32_e32 v195, 0xbfb8aa3b, v195
	v_mul_f32_e32 v235, 0xbfb8aa3b, v235
	v_mul_f32_e32 v155, 0xbfb8aa3b, v236
	v_exp_f32_e32 v232, v232
	v_exp_f32_e32 v233, v233
	v_mul_f32_e32 v194, 0xbfb8aa3b, v194
	v_mul_f32_e32 v234, 0xbfb8aa3b, v234
	v_exp_f32_e32 v195, v195
	v_exp_f32_e32 v235, v235
	v_exp_f32_e32 v151, v151
	v_exp_f32_e32 v155, v155
	v_exp_f32_e32 v194, v194
	v_exp_f32_e32 v234, v234
	v_add_f32_e32 v232, 1.0, v232
	v_add_f32_e32 v233, 1.0, v233
	v_add_f32_e32 v195, 1.0, v195
	v_add_f32_e32 v235, 1.0, v235
	v_add_f32_e32 v151, 1.0, v151
	v_add_f32_e32 v155, 1.0, v155
	v_rcp_f32_e32 v232, v232
	v_rcp_f32_e32 v233, v233
	v_add_f32_e32 v194, 1.0, v194
	v_add_f32_e32 v234, 1.0, v234
	v_rcp_f32_e32 v195, v195
	v_rcp_f32_e32 v235, v235
	v_rcp_f32_e32 v151, v151
	v_rcp_f32_e32 v155, v155
	v_rcp_f32_e32 v194, v194
	v_rcp_f32_e32 v234, v234
	v_lshlrev_b32_e32 v236, 16, v182
	v_and_b32_e32 v182, 0xffff0000, v182
	v_lshlrev_b32_e32 v237, 16, v183
	v_and_b32_e32 v183, 0xffff0000, v183
	v_and_b32_e32 v185, 0xffff0000, v185
	s_waitcnt vmcnt(6)
	v_lshlrev_b32_e32 v240, 16, v186
	v_and_b32_e32 v186, 0xffff0000, v186
	v_lshlrev_b32_e32 v241, 16, v187
	v_and_b32_e32 v187, 0xffff0000, v187
	v_lshlrev_b32_e32 v242, 16, v188
	v_and_b32_e32 v188, 0xffff0000, v188
	v_lshlrev_b32_e32 v243, 16, v189
	v_and_b32_e32 v189, 0xffff0000, v189
	v_fmac_f32_e32 v182, v232, v186
	v_fmac_f32_e32 v184, v233, v188
	v_fmac_f32_e32 v183, v195, v187
	v_fmac_f32_e32 v185, v235, v189
	v_fmac_f32_e32 v236, v151, v240
	v_fmac_f32_e32 v238, v155, v242
	v_fmac_f32_e32 v237, v194, v241
	v_fmac_f32_e32 v239, v234, v243
	v_cvt_pk_bf16_f32 v182, v236, v182
	v_cvt_pk_bf16_f32 v183, v237, v183
	v_cvt_pk_bf16_f32 v184, v238, v184
	v_cvt_pk_bf16_f32 v185, v239, v185
	global_store_dwordx4 v[148:149], v[182:185], off
	v_lshlrev_b32_e32 v186, 16, v182
	v_and_b32_e32 v187, 0xffff0000, v182
	v_lshlrev_b32_e32 v182, 16, v183
	v_and_b32_e32 v183, 0xffff0000, v183
	v_lshlrev_b32_e32 v188, 16, v184
	v_and_b32_e32 v189, 0xffff0000, v184
	v_lshlrev_b32_e32 v184, 16, v185
	v_and_b32_e32 v185, 0xffff0000, v185
	v_pk_mul_f32 v[184:185], v[184:185], v[184:185]
	v_pk_mul_f32 v[182:183], v[182:183], v[182:183]
	v_pk_mul_f32 v[186:187], v[186:187], v[186:187]
	v_add_f32_e32 v155, v182, v183
	v_add_f32_e32 v151, v186, v187
	v_add_f32_e32 v182, v184, v185
	v_pk_mul_f32 v[184:185], v[156:157], v[116:117] op_sel_hi:[0,1]
	v_pk_mul_f32 v[186:187], v[156:157], v[112:113] op_sel_hi:[0,1]
	v_mul_f32_e32 v184, 0xbfb8aa3b, v184
	v_mul_f32_e32 v186, 0xbfb8aa3b, v186
	v_exp_f32_e32 v184, v184
	v_exp_f32_e32 v186, v186
	v_pk_mul_f32 v[188:189], v[188:189], v[188:189]
	v_add_f32_e32 v151, v151, v155
	v_add_f32_e32 v155, v188, v189
	v_add_f32_e32 v155, v155, v182
	v_pk_mul_f32 v[182:183], v[156:157], v[118:119] op_sel_hi:[0,1]
	v_pk_mul_f32 v[188:189], v[156:157], v[114:115] op_sel_hi:[0,1]
	v_add_f32_e32 v156, 1.0, v184
	v_add_f32_e32 v184, 1.0, v186
	v_mul_f32_e32 v185, 0xbfb8aa3b, v185
	v_mul_f32_e32 v186, 0xbfb8aa3b, v187
	v_mul_f32_e32 v182, 0xbfb8aa3b, v182
	v_mul_f32_e32 v187, 0xbfb8aa3b, v188
	v_mul_f32_e32 v183, 0xbfb8aa3b, v183
	v_mul_f32_e32 v188, 0xbfb8aa3b, v189
	v_exp_f32_e32 v185, v185
	v_exp_f32_e32 v186, v186
	v_exp_f32_e32 v182, v182
	v_exp_f32_e32 v187, v187
	v_exp_f32_e32 v183, v183
	v_exp_f32_e32 v188, v188
	v_add_f32_e32 v185, 1.0, v185
	v_add_f32_e32 v186, 1.0, v186
	v_add_f32_e32 v182, 1.0, v182
	v_add_f32_e32 v187, 1.0, v187
	v_add_f32_e32 v183, 1.0, v183
	v_add_f32_e32 v188, 1.0, v188
	v_rcp_f32_e32 v156, v156
	v_rcp_f32_e32 v185, v185
	v_rcp_f32_e32 v186, v186
	v_rcp_f32_e32 v182, v182
	v_rcp_f32_e32 v187, v187
	v_rcp_f32_e32 v183, v183
	v_rcp_f32_e32 v188, v188
	v_rcp_f32_e32 v184, v184
	v_add_f32_e32 v151, v151, v155
	s_waitcnt vmcnt(6)
	v_lshlrev_b32_e32 v155, 16, v190
	v_and_b32_e32 v190, 0xffff0000, v190
	v_lshlrev_b32_e32 v194, 16, v191
	v_and_b32_e32 v191, 0xffff0000, v191
	v_lshlrev_b32_e32 v195, 16, v192
	v_and_b32_e32 v192, 0xffff0000, v192
	v_lshlrev_b32_e32 v232, 16, v193
	v_and_b32_e32 v193, 0xffff0000, v193
	s_waitcnt vmcnt(5)
	v_lshlrev_b32_e32 v233, 16, v202
	v_and_b32_e32 v202, 0xffff0000, v202
	v_lshlrev_b32_e32 v234, 16, v203
	v_and_b32_e32 v203, 0xffff0000, v203
	v_lshlrev_b32_e32 v235, 16, v204
	v_and_b32_e32 v204, 0xffff0000, v204
	v_lshlrev_b32_e32 v236, 16, v205
	v_and_b32_e32 v205, 0xffff0000, v205
	v_fmac_f32_e32 v155, v156, v233
	v_fmac_f32_e32 v190, v185, v202
	v_fmac_f32_e32 v192, v186, v204
	v_fmac_f32_e32 v194, v182, v234
	v_fmac_f32_e32 v232, v187, v236
	v_fmac_f32_e32 v191, v183, v203
	v_fmac_f32_e32 v193, v188, v205
	v_cvt_pk_bf16_f32 v182, v155, v190
	v_cvt_pk_bf16_f32 v183, v194, v191
	v_fmac_f32_e32 v195, v184, v235
	v_lshlrev_b32_e32 v186, 16, v182
	v_and_b32_e32 v187, 0xffff0000, v182
	v_lshlrev_b32_e32 v188, 16, v183
	v_and_b32_e32 v189, 0xffff0000, v183
	v_cvt_pk_bf16_f32 v184, v195, v192
	v_cvt_pk_bf16_f32 v185, v232, v193
	v_pk_mul_f32 v[188:189], v[188:189], v[188:189]
	v_lshlrev_b32_e32 v190, 16, v184
	v_and_b32_e32 v191, 0xffff0000, v184
	v_lshlrev_b32_e32 v192, 16, v185
	v_and_b32_e32 v193, 0xffff0000, v185
	v_pk_mul_f32 v[186:187], v[186:187], v[186:187]
	v_pk_mul_f32 v[192:193], v[192:193], v[192:193]
	v_pk_mul_f32 v[190:191], v[190:191], v[190:191]
	v_add_f32_e32 v155, v186, v187
	v_add_f32_e32 v156, v188, v189
	v_add_f32_e32 v155, v155, v156
	v_add_f32_e32 v156, v190, v191
	v_add_f32_e32 v186, v192, v193
	v_add_f32_e32 v156, v156, v186
	v_add_f32_e32 v155, v155, v156
	v_add_f32_e32 v151, v151, v155
	ds_bpermute_b32 v155, v215, v151
	v_cmp_gt_f32_e32 vcc, s37, v150
	global_store_dwordx4 v[148:149], v[182:185], off offset:256
	v_lshl_add_u64 v[148:149], v[144:145], 3, s[4:5]
	s_waitcnt lgkmcnt(0)
	v_add_f32_e32 v151, v151, v155
	ds_bpermute_b32 v155, v216, v151
	s_and_saveexec_b64 s[2:3], s[38:39]
	s_cbranch_execz .LBB0_459
	s_waitcnt lgkmcnt(0)
	v_add_f32_e32 v151, v151, v155
	v_mul_f32_e32 v151, 0x49800000, v151
	v_trunc_f32_e32 v151, v151
	v_mul_f32_e32 v155, 0x2f800000, v151
	v_floor_f32_e32 v155, v155
	v_fmac_f32_e32 v151, 0xcf800000, v155
	v_cvt_u32_f32_e32 v182, v151
	v_cvt_u32_f32_e32 v183, v155
	global_atomic_add_x2 v[148:149], v[182:183], off

.LBB0_491:
	v_ashrrev_i32_e32 v147, 31, v146
	s_waitcnt lgkmcnt(0)
	v_ashrrev_i32_e32 v129, 31, v144
	v_lshl_add_u64 v[132:133], v[146:147], 1, s[30:31]
	v_mul_lo_u32 v129, s14, v129
	v_mul_lo_u32 v131, s15, v144
	v_mad_u64_u32 v[146:147], s[2:3], s14, v144, 0
	v_add3_u32 v147, v147, v129, v131
	v_lshl_add_u64 v[146:147], v[146:147], 1, v[132:133]
	v_pk_mul_f32 v[126:127], v[126:127], v[148:149] op_sel_hi:[1,0]
	v_pk_mul_f32 v[124:125], v[124:125], v[148:149] op_sel_hi:[1,0]
	v_pk_mul_f32 v[150:151], v[122:123], v[148:149] op_sel_hi:[1,0]
	v_pk_mul_f32 v[122:123], v[120:121], v[148:149] op_sel_hi:[1,0]
	v_cvt_pk_bf16_f32 v120, v124, v125
	v_cvt_pk_bf16_f32 v121, v126, v127
	v_pk_mul_f32 v[116:117], v[116:117], v[148:149] op_sel_hi:[1,0]
	v_cvt_pk_bf16_f32 v122, v122, v123
	v_cvt_pk_bf16_f32 v123, v150, v151
	global_store_dwordx4 v[146:147], v[120:123], off
	v_pk_mul_f32 v[118:119], v[118:119], v[148:149] op_sel_hi:[1,0]
	v_pk_mul_f32 v[110:111], v[110:111], v[142:143] op_sel_hi:[1,0]
	v_pk_mul_f32 v[120:121], v[114:115], v[148:149] op_sel_hi:[1,0]
	v_pk_mul_f32 v[114:115], v[112:113], v[148:149] op_sel_hi:[1,0]
	v_cvt_pk_bf16_f32 v112, v116, v117
	v_cvt_pk_bf16_f32 v113, v118, v119
	v_pk_mul_f32 v[108:109], v[108:109], v[142:143] op_sel_hi:[1,0]
	v_cvt_pk_bf16_f32 v114, v114, v115
	v_cvt_pk_bf16_f32 v115, v120, v121
	global_store_dwordx4 v[146:147], v[112:115], off offset:256
	v_pk_mul_f32 v[100:101], v[100:101], v[142:143] op_sel_hi:[1,0]
	v_pk_mul_f32 v[102:103], v[102:103], v[142:143] op_sel_hi:[1,0]
	v_or_b32_e32 v112, 16, v144
	v_mul_lo_u32 v114, s15, v112
	v_mad_u64_u32 v[112:113], s[2:3], s14, v112, 0
	v_add3_u32 v113, v113, v129, v114
	v_lshl_add_u64 v[112:113], v[112:113], 1, v[132:133]
	v_pk_mul_f32 v[114:115], v[106:107], v[142:143] op_sel_hi:[1,0]
	v_pk_mul_f32 v[106:107], v[104:105], v[142:143] op_sel_hi:[1,0]
	v_cvt_pk_bf16_f32 v104, v108, v109
	v_cvt_pk_bf16_f32 v105, v110, v111
	v_pk_mul_f32 v[94:95], v[94:95], v[140:141] op_sel_hi:[1,0]
	v_cvt_pk_bf16_f32 v106, v106, v107
	v_cvt_pk_bf16_f32 v107, v114, v115
	global_store_dwordx4 v[112:113], v[104:107], off
	v_pk_mul_f32 v[92:93], v[92:93], v[140:141] op_sel_hi:[1,0]
	v_pk_mul_f32 v[84:85], v[84:85], v[140:141] op_sel_hi:[1,0]
	v_pk_mul_f32 v[104:105], v[98:99], v[142:143] op_sel_hi:[1,0]
	v_pk_mul_f32 v[98:99], v[96:97], v[142:143] op_sel_hi:[1,0]
	v_cvt_pk_bf16_f32 v96, v100, v101
	v_cvt_pk_bf16_f32 v97, v102, v103
	v_pk_mul_f32 v[86:87], v[86:87], v[140:141] op_sel_hi:[1,0]
	v_cvt_pk_bf16_f32 v98, v98, v99
	v_cvt_pk_bf16_f32 v99, v104, v105
	global_store_dwordx4 v[112:113], v[96:99], off offset:256
	v_pk_mul_f32 v[78:79], v[78:79], v[138:139] op_sel_hi:[1,0]
	v_pk_mul_f32 v[76:77], v[76:77], v[138:139] op_sel_hi:[1,0]
	v_or_b32_e32 v96, 32, v144
	v_mul_lo_u32 v98, s15, v96
	v_mad_u64_u32 v[96:97], s[2:3], s14, v96, 0
	v_add3_u32 v97, v97, v129, v98
	v_lshl_add_u64 v[96:97], v[96:97], 1, v[132:133]
	v_pk_mul_f32 v[98:99], v[90:91], v[140:141] op_sel_hi:[1,0]
	v_pk_mul_f32 v[90:91], v[88:89], v[140:141] op_sel_hi:[1,0]
	v_cvt_pk_bf16_f32 v88, v92, v93
	v_cvt_pk_bf16_f32 v89, v94, v95
	v_pk_mul_f32 v[68:69], v[68:69], v[138:139] op_sel_hi:[1,0]
	v_cvt_pk_bf16_f32 v90, v90, v91
	v_cvt_pk_bf16_f32 v91, v98, v99
	global_store_dwordx4 v[96:97], v[88:91], off
	v_pk_mul_f32 v[70:71], v[70:71], v[138:139] op_sel_hi:[1,0]
	v_pk_mul_f32 v[62:63], v[62:63], v[136:137] op_sel_hi:[1,0]
	v_pk_mul_f32 v[88:89], v[82:83], v[140:141] op_sel_hi:[1,0]
	v_pk_mul_f32 v[82:83], v[80:81], v[140:141] op_sel_hi:[1,0]
	v_cvt_pk_bf16_f32 v80, v84, v85
	v_cvt_pk_bf16_f32 v81, v86, v87
	v_pk_mul_f32 v[60:61], v[60:61], v[136:137] op_sel_hi:[1,0]
	v_cvt_pk_bf16_f32 v82, v82, v83
	v_cvt_pk_bf16_f32 v83, v88, v89
	global_store_dwordx4 v[96:97], v[80:83], off offset:256
	v_pk_mul_f32 v[52:53], v[52:53], v[136:137] op_sel_hi:[1,0]
	v_pk_mul_f32 v[54:55], v[54:55], v[136:137] op_sel_hi:[1,0]
	v_or_b32_e32 v80, 48, v144
	v_mul_lo_u32 v82, s15, v80
	v_mad_u64_u32 v[80:81], s[2:3], s14, v80, 0
	v_add3_u32 v81, v81, v129, v82
	v_lshl_add_u64 v[80:81], v[80:81], 1, v[132:133]
	v_pk_mul_f32 v[82:83], v[74:75], v[138:139] op_sel_hi:[1,0]
	v_pk_mul_f32 v[74:75], v[72:73], v[138:139] op_sel_hi:[1,0]
	v_cvt_pk_bf16_f32 v72, v76, v77
	v_cvt_pk_bf16_f32 v73, v78, v79
	v_pk_mul_f32 v[46:47], v[46:47], v[134:135] op_sel_hi:[1,0]
	v_cvt_pk_bf16_f32 v74, v74, v75
	v_cvt_pk_bf16_f32 v75, v82, v83
	global_store_dwordx4 v[80:81], v[72:75], off
	v_pk_mul_f32 v[44:45], v[44:45], v[134:135] op_sel_hi:[1,0]
	v_pk_mul_f32 v[36:37], v[36:37], v[134:135] op_sel_hi:[1,0]
	v_pk_mul_f32 v[72:73], v[66:67], v[138:139] op_sel_hi:[1,0]
	v_pk_mul_f32 v[66:67], v[64:65], v[138:139] op_sel_hi:[1,0]
	v_cvt_pk_bf16_f32 v64, v68, v69
	v_cvt_pk_bf16_f32 v65, v70, v71
	v_pk_mul_f32 v[38:39], v[38:39], v[134:135] op_sel_hi:[1,0]
	v_cvt_pk_bf16_f32 v66, v66, v67
	v_cvt_pk_bf16_f32 v67, v72, v73
	global_store_dwordx4 v[80:81], v[64:67], off offset:256
	s_cmp_lt_i32 s100, 0
	s_cbranch_scc1 .LBB0_492
	v_pk_mul_f32 v[30:31], v[30:31], v[130:131] op_sel_hi:[1,0]
	v_pk_mul_f32 v[28:29], v[28:29], v[130:131] op_sel_hi:[1,0]
	v_add_u32_e32 v64, 0x80, v144
	v_ashrrev_i32_e32 v65, 31, v64
	v_mul_lo_u32 v66, s14, v65
	v_mul_lo_u32 v67, s15, v64
	v_mad_u64_u32 v[64:65], s[2:3], s14, v64, 0
	v_add3_u32 v65, v65, v66, v67
	v_lshl_add_u64 v[64:65], v[64:65], 1, v[132:133]
	v_pk_mul_f32 v[66:67], v[58:59], v[136:137] op_sel_hi:[1,0]
	v_pk_mul_f32 v[58:59], v[56:57], v[136:137] op_sel_hi:[1,0]
	v_cvt_pk_bf16_f32 v56, v60, v61
	v_cvt_pk_bf16_f32 v57, v62, v63
	v_pk_mul_f32 v[20:21], v[20:21], v[130:131] op_sel_hi:[1,0]
	v_cvt_pk_bf16_f32 v58, v58, v59
	v_cvt_pk_bf16_f32 v59, v66, v67
	global_store_dwordx4 v[64:65], v[56:59], off
	v_pk_mul_f32 v[22:23], v[22:23], v[130:131] op_sel_hi:[1,0]
	v_pk_mul_f32 v[14:15], v[14:15], v[128:129] op_sel_hi:[1,0]
	v_pk_mul_f32 v[56:57], v[50:51], v[136:137] op_sel_hi:[1,0]
	v_pk_mul_f32 v[50:51], v[48:49], v[136:137] op_sel_hi:[1,0]
	v_cvt_pk_bf16_f32 v48, v52, v53
	v_cvt_pk_bf16_f32 v49, v54, v55
	v_pk_mul_f32 v[12:13], v[12:13], v[128:129] op_sel_hi:[1,0]
	v_cvt_pk_bf16_f32 v50, v50, v51
	v_cvt_pk_bf16_f32 v51, v56, v57
	global_store_dwordx4 v[64:65], v[48:51], off offset:256
	v_pk_mul_f32 v[6:7], v[6:7], v[128:129] op_sel_hi:[1,0]
	v_pk_mul_f32 v[4:5], v[4:5], v[128:129] op_sel_hi:[1,0]
	v_add_u32_e32 v48, 0x90, v144
	v_ashrrev_i32_e32 v49, 31, v48
	v_mul_lo_u32 v50, s14, v49
	v_mul_lo_u32 v51, s15, v48
	v_mad_u64_u32 v[48:49], s[2:3], s14, v48, 0
	v_add3_u32 v49, v49, v50, v51
	v_lshl_add_u64 v[48:49], v[48:49], 1, v[132:133]
	v_pk_mul_f32 v[50:51], v[42:43], v[134:135] op_sel_hi:[1,0]
	v_pk_mul_f32 v[42:43], v[40:41], v[134:135] op_sel_hi:[1,0]
	v_cvt_pk_bf16_f32 v40, v44, v45
	v_cvt_pk_bf16_f32 v41, v46, v47
	s_nop 0
	v_cvt_pk_bf16_f32 v42, v42, v43
	v_cvt_pk_bf16_f32 v43, v50, v51
	global_store_dwordx4 v[48:49], v[40:43], off
	s_nop 1
	v_pk_mul_f32 v[40:41], v[34:35], v[134:135] op_sel_hi:[1,0]
	v_pk_mul_f32 v[34:35], v[32:33], v[134:135] op_sel_hi:[1,0]
	v_cvt_pk_bf16_f32 v32, v36, v37
	v_cvt_pk_bf16_f32 v33, v38, v39
	s_nop 0
	v_cvt_pk_bf16_f32 v34, v34, v35
	v_cvt_pk_bf16_f32 v35, v40, v41
	global_store_dwordx4 v[48:49], v[32:35], off offset:256
	s_nop 1
	v_add_u32_e32 v32, 0xa0, v144
	v_ashrrev_i32_e32 v33, 31, v32
	v_mul_lo_u32 v34, s14, v33
	v_mul_lo_u32 v35, s15, v32
	v_mad_u64_u32 v[32:33], s[2:3], s14, v32, 0
	v_add3_u32 v33, v33, v34, v35
	v_lshl_add_u64 v[32:33], v[32:33], 1, v[132:133]
	v_pk_mul_f32 v[34:35], v[26:27], v[130:131] op_sel_hi:[1,0]
	v_pk_mul_f32 v[26:27], v[24:25], v[130:131] op_sel_hi:[1,0]
	v_cvt_pk_bf16_f32 v24, v28, v29
	v_cvt_pk_bf16_f32 v25, v30, v31
	s_nop 0
	v_cvt_pk_bf16_f32 v26, v26, v27
	v_cvt_pk_bf16_f32 v27, v34, v35
	global_store_dwordx4 v[32:33], v[24:27], off
	s_nop 1
	v_pk_mul_f32 v[24:25], v[18:19], v[130:131] op_sel_hi:[1,0]
	v_pk_mul_f32 v[18:19], v[16:17], v[130:131] op_sel_hi:[1,0]
	v_cvt_pk_bf16_f32 v16, v20, v21
	v_cvt_pk_bf16_f32 v17, v22, v23
	s_nop 0
	v_cvt_pk_bf16_f32 v18, v18, v19
	v_cvt_pk_bf16_f32 v19, v24, v25
	global_store_dwordx4 v[32:33], v[16:19], off offset:256
	s_nop 1
	v_add_u32_e32 v16, 0xb0, v144
	v_ashrrev_i32_e32 v17, 31, v16
	v_mul_lo_u32 v18, s14, v17
	v_mul_lo_u32 v19, s15, v16
	v_mad_u64_u32 v[16:17], s[2:3], s14, v16, 0
	v_add3_u32 v17, v17, v18, v19
	v_lshl_add_u64 v[16:17], v[16:17], 1, v[132:133]
	v_pk_mul_f32 v[18:19], v[10:11], v[128:129] op_sel_hi:[1,0]
	v_pk_mul_f32 v[10:11], v[8:9], v[128:129] op_sel_hi:[1,0]
	v_cvt_pk_bf16_f32 v8, v12, v13
	v_cvt_pk_bf16_f32 v9, v14, v15
	s_nop 0
	v_cvt_pk_bf16_f32 v10, v10, v11
	v_cvt_pk_bf16_f32 v11, v18, v19
	global_store_dwordx4 v[16:17], v[8:11], off
	s_nop 1
	v_pk_mul_f32 v[8:9], v[2:3], v[128:129] op_sel_hi:[1,0]
	v_pk_mul_f32 v[2:3], v[0:1], v[128:129] op_sel_hi:[1,0]
	v_cvt_pk_bf16_f32 v0, v4, v5
	v_cvt_pk_bf16_f32 v1, v6, v7
	s_nop 0
	v_cvt_pk_bf16_f32 v2, v2, v3
	v_cvt_pk_bf16_f32 v3, v8, v9
	global_store_dwordx4 v[16:17], v[0:3], off offset:256
.LBB0_492:
	s_and_b64 vcc, exec, s[40:41]
	s_mov_b64 s[2:3], -1
	s_cbranch_vccnz .LBB0_264
	s_and_b64 vcc, exec, s[42:43]
	s_cbranch_vccnz .LBB0_495
	s_lshl_b32 s2, s23, 8
	s_cmp_eq_u32 s24, 18
	s_cbranch_scc0 .Lms_d
	s_cmp_eq_u32 s80, 0x100
	s_cbranch_scc0 .Lms_d
	s_cmp_eq_u32 s0, 4
	s_cbranch_scc0 .Lms_d
	s_cmp_lt_u32 s12, 0x80
	s_cbranch_scc1 .Lms_d
	s_addk_i32 s2, 0x80
.Lms_d:
	s_ashr_i32 s3, s2, 31
	v_lshl_add_u64 v[0:1], s[2:3], 3, v[164:165]
	global_load_dwordx2 v[180:181], v[0:1], off
	global_load_dwordx2 v[178:179], v[0:1], off offset:128
	global_load_dwordx2 v[176:177], v[0:1], off offset:256
	global_load_dwordx2 v[174:175], v[0:1], off offset:384
	global_load_dwordx2 v[172:173], v[0:1], off offset:1024
	global_load_dwordx2 v[170:171], v[0:1], off offset:1152
	global_load_dwordx2 v[168:169], v[0:1], off offset:1280
	global_load_dwordx2 v[166:167], v[0:1], off offset:1408
	s_andn2_b64 vcc, exec, s[52:53]
	s_cbranch_vccnz .LBB0_263
	s_branch .LBB0_262
